# counted lgkmcnt waits in the 256x128 GEMM K-loops (gemm1, mlp1): B fragments read first, each MFMA group waits only for its own A fragment
# speedup vs baseline: 1.0070x; 1.0070x over previous
.LBB0_189:
	s_mul_i32 s8, s3, 0x6000
	s_add_i32 s8, s8, 0
	s_waitcnt vmcnt(6)
	v_add3_u32 v149, s8, v143, v142
	s_waitcnt lgkmcnt(0)
	s_barrier
	v_add3_u32 v248, s8, v144, v142
	ds_read_b128 v[182:185], v248 offset:16384
	ds_read_b128 v[186:189], v248 offset:17408
	ds_read_b128 v[190:193], v248 offset:18432
	ds_read_b128 v[194:197], v248 offset:19456
	ds_read_b128 v[150:153], v149
	ds_read_b128 v[154:157], v149 offset:1024
	ds_read_b128 v[158:161], v149 offset:2048
	ds_read_b128 v[162:165], v149 offset:3072
	ds_read_b128 v[166:169], v149 offset:4096
	ds_read_b128 v[170:173], v149 offset:5120
	ds_read_b128 v[174:177], v149 offset:6144
	ds_read_b128 v[178:181], v149 offset:7168
	s_cmp_gt_i32 s3, 0
	s_cselect_b32 s8, -1, 2
	s_add_i32 s8, s8, s3
	s_mulk_i32 s8, 0x6000
	v_lshl_add_u64 v[198:199], v[140:141], 0, s[6:7]
	s_add_i32 s8, s2, s8
	v_lshl_add_u64 v[200:201], v[198:199], 0, s[12:13]
	s_mov_b32 m0, s8
	s_mov_b64 s[10:11], 0x200080
	global_load_lds_dwordx4 v[200:201], off
	v_lshl_add_u64 v[200:201], v[198:199], 0, s[14:15]
	s_add_i32 m0, s8, 0x1000
	s_nop 0
	global_load_lds_dwordx4 v[200:201], off
	v_lshl_add_u64 v[200:201], v[198:199], 0, s[28:29]
	s_add_i32 m0, s8, 0x2000
	v_lshl_add_u64 v[198:199], v[198:199], 0, s[30:31]
	global_load_lds_dwordx4 v[200:201], off
	s_add_i32 m0, s8, 0x3000
	s_nop 0
	global_load_lds_dwordx4 v[198:199], off
	v_lshl_add_u64 v[198:199], v[138:139], 0, s[6:7]
	v_lshl_add_u64 v[200:201], v[198:199], 0, s[10:11]
	s_add_i32 m0, s8, 0x4000
	s_mov_b64 s[10:11], 0x220080
	global_load_lds_dwordx4 v[200:201], off
	v_lshl_add_u64 v[198:199], v[198:199], 0, s[10:11]
	s_add_i32 m0, s8, 0x5000
	s_nop 0
	global_load_lds_dwordx4 v[198:199], off
	s_setprio 1
	s_waitcnt lgkmcnt(7)
	v_mfma_f32_16x16x32_bf16 v[126:129], v[182:185], v[150:153], v[126:129]
	v_mfma_f32_16x16x32_bf16 v[122:125], v[186:189], v[150:153], v[122:125]
	v_mfma_f32_16x16x32_bf16 v[118:121], v[190:193], v[150:153], v[118:121]
	v_mfma_f32_16x16x32_bf16 v[114:117], v[194:197], v[150:153], v[114:117]
	s_waitcnt lgkmcnt(6)
	v_mfma_f32_16x16x32_bf16 v[110:113], v[182:185], v[154:157], v[110:113]
	v_mfma_f32_16x16x32_bf16 v[106:109], v[186:189], v[154:157], v[106:109]
	v_mfma_f32_16x16x32_bf16 v[102:105], v[190:193], v[154:157], v[102:105]
	v_mfma_f32_16x16x32_bf16 v[98:101], v[194:197], v[154:157], v[98:101]
	s_waitcnt lgkmcnt(5)
	v_mfma_f32_16x16x32_bf16 v[94:97], v[182:185], v[158:161], v[94:97]
	v_mfma_f32_16x16x32_bf16 v[90:93], v[186:189], v[158:161], v[90:93]
	v_mfma_f32_16x16x32_bf16 v[86:89], v[190:193], v[158:161], v[86:89]
	v_mfma_f32_16x16x32_bf16 v[82:85], v[194:197], v[158:161], v[82:85]
	s_waitcnt lgkmcnt(4)
	v_mfma_f32_16x16x32_bf16 v[78:81], v[182:185], v[162:165], v[78:81]
	v_mfma_f32_16x16x32_bf16 v[74:77], v[186:189], v[162:165], v[74:77]
	v_mfma_f32_16x16x32_bf16 v[70:73], v[190:193], v[162:165], v[70:73]
	v_mfma_f32_16x16x32_bf16 v[66:69], v[194:197], v[162:165], v[66:69]
	s_waitcnt lgkmcnt(3)
	v_mfma_f32_16x16x32_bf16 v[62:65], v[182:185], v[166:169], v[62:65]
	v_mfma_f32_16x16x32_bf16 v[58:61], v[186:189], v[166:169], v[58:61]
	v_mfma_f32_16x16x32_bf16 v[54:57], v[190:193], v[166:169], v[54:57]
	v_mfma_f32_16x16x32_bf16 v[50:53], v[194:197], v[166:169], v[50:53]
	s_waitcnt lgkmcnt(2)
	v_mfma_f32_16x16x32_bf16 v[46:49], v[182:185], v[170:173], v[46:49]
	v_mfma_f32_16x16x32_bf16 v[42:45], v[186:189], v[170:173], v[42:45]
	v_mfma_f32_16x16x32_bf16 v[38:41], v[190:193], v[170:173], v[38:41]
	v_mfma_f32_16x16x32_bf16 v[34:37], v[194:197], v[170:173], v[34:37]
	s_waitcnt lgkmcnt(1)
	v_mfma_f32_16x16x32_bf16 v[30:33], v[182:185], v[174:177], v[30:33]
	v_mfma_f32_16x16x32_bf16 v[26:29], v[186:189], v[174:177], v[26:29]
	v_mfma_f32_16x16x32_bf16 v[22:25], v[190:193], v[174:177], v[22:25]
	v_mfma_f32_16x16x32_bf16 v[18:21], v[194:197], v[174:177], v[18:21]
	s_waitcnt lgkmcnt(0)
	v_mfma_f32_16x16x32_bf16 v[14:17], v[182:185], v[178:181], v[14:17]
	v_mfma_f32_16x16x32_bf16 v[10:13], v[186:189], v[178:181], v[10:13]
	v_mfma_f32_16x16x32_bf16 v[6:9], v[190:193], v[178:181], v[6:9]
	v_mfma_f32_16x16x32_bf16 v[2:5], v[194:197], v[178:181], v[2:5]
	s_setprio 0
	s_add_i32 s3, s3, 1
	s_cmp_lg_u32 s3, 3
	s_cselect_b32 s3, s3, 0
	s_add_u32 s6, s6, 64
	s_addc_u32 s7, s7, 0
	s_cmpk_lg_i32 s6, 0x780
	s_cbranch_scc1 .LBB0_189
	s_waitcnt vmcnt(6)
	s_waitcnt lgkmcnt(0)
	s_barrier
	ds_read_b128 v[138:141], v147
	ds_read_b128 v[150:153], v147 offset:1024
	ds_read_b128 v[154:157], v147 offset:2048
	ds_read_b128 v[158:161], v147 offset:3072
	ds_read_b128 v[162:165], v147 offset:4096
	ds_read_b128 v[166:169], v147 offset:5120
	ds_read_b128 v[170:173], v147 offset:6144
	ds_read_b128 v[174:177], v147 offset:7168
	ds_read_b128 v[178:181], v148 offset:16384
	ds_read_b128 v[182:185], v148 offset:17408
	ds_read_b128 v[186:189], v148 offset:18432
	ds_read_b128 v[190:193], v148 offset:19456
	s_setprio 1
	s_waitcnt lgkmcnt(0)
	v_mfma_f32_16x16x32_bf16 v[126:129], v[178:181], v[138:141], v[126:129]
	v_mfma_f32_16x16x32_bf16 v[122:125], v[182:185], v[138:141], v[122:125]
	v_mfma_f32_16x16x32_bf16 v[118:121], v[186:189], v[138:141], v[118:121]
	v_mfma_f32_16x16x32_bf16 v[114:117], v[190:193], v[138:141], v[114:117]
	v_mfma_f32_16x16x32_bf16 v[110:113], v[178:181], v[150:153], v[110:113]
	v_mfma_f32_16x16x32_bf16 v[106:109], v[182:185], v[150:153], v[106:109]
	v_mfma_f32_16x16x32_bf16 v[102:105], v[186:189], v[150:153], v[102:105]
	v_mfma_f32_16x16x32_bf16 v[98:101], v[190:193], v[150:153], v[98:101]
	v_mfma_f32_16x16x32_bf16 v[94:97], v[178:181], v[154:157], v[94:97]
	v_mfma_f32_16x16x32_bf16 v[90:93], v[182:185], v[154:157], v[90:93]
	v_mfma_f32_16x16x32_bf16 v[86:89], v[186:189], v[154:157], v[86:89]
	v_mfma_f32_16x16x32_bf16 v[82:85], v[190:193], v[154:157], v[82:85]
	v_mfma_f32_16x16x32_bf16 v[78:81], v[178:181], v[158:161], v[78:81]
	v_mfma_f32_16x16x32_bf16 v[74:77], v[182:185], v[158:161], v[74:77]
	v_mfma_f32_16x16x32_bf16 v[70:73], v[186:189], v[158:161], v[70:73]
	v_mfma_f32_16x16x32_bf16 v[66:69], v[190:193], v[158:161], v[66:69]
	v_mfma_f32_16x16x32_bf16 v[62:65], v[178:181], v[162:165], v[62:65]
	v_mfma_f32_16x16x32_bf16 v[58:61], v[182:185], v[162:165], v[58:61]
	v_mfma_f32_16x16x32_bf16 v[54:57], v[186:189], v[162:165], v[54:57]
	v_mfma_f32_16x16x32_bf16 v[50:53], v[190:193], v[162:165], v[50:53]
	v_mfma_f32_16x16x32_bf16 v[46:49], v[178:181], v[166:169], v[46:49]
	v_mfma_f32_16x16x32_bf16 v[42:45], v[182:185], v[166:169], v[42:45]
	v_mfma_f32_16x16x32_bf16 v[38:41], v[186:189], v[166:169], v[38:41]
	v_mfma_f32_16x16x32_bf16 v[34:37], v[190:193], v[166:169], v[34:37]
	v_mfma_f32_16x16x32_bf16 v[30:33], v[178:181], v[170:173], v[30:33]
	v_mfma_f32_16x16x32_bf16 v[26:29], v[182:185], v[170:173], v[26:29]
	v_mfma_f32_16x16x32_bf16 v[22:25], v[186:189], v[170:173], v[22:25]
	v_mfma_f32_16x16x32_bf16 v[18:21], v[190:193], v[170:173], v[18:21]
	v_mfma_f32_16x16x32_bf16 v[14:17], v[178:181], v[174:177], v[14:17]
	v_mfma_f32_16x16x32_bf16 v[10:13], v[182:185], v[174:177], v[10:13]
	v_mfma_f32_16x16x32_bf16 v[6:9], v[186:189], v[174:177], v[6:9]
	v_mfma_f32_16x16x32_bf16 v[2:5], v[190:193], v[174:177], v[2:5]
	s_setprio 0
	s_waitcnt vmcnt(0)
	s_waitcnt lgkmcnt(0)
	s_barrier
	ds_read_b128 v[138:141], v147 offset:24576
	ds_read_b128 v[150:153], v147 offset:25600
	ds_read_b128 v[154:157], v147 offset:26624
	ds_read_b128 v[158:161], v147 offset:27648
	ds_read_b128 v[162:165], v147 offset:28672
	ds_read_b128 v[166:169], v147 offset:29696
	ds_read_b128 v[170:173], v147 offset:30720
	ds_read_b128 v[174:177], v147 offset:31744
	ds_read_b128 v[178:181], v148 offset:40960
	ds_read_b128 v[182:185], v148 offset:41984
	ds_read_b128 v[186:189], v148 offset:43008
	ds_read_b128 v[190:193], v148 offset:44032
	s_setprio 1
	s_waitcnt lgkmcnt(0)
	v_mfma_f32_16x16x32_bf16 v[126:129], v[178:181], v[138:141], v[126:129]
	v_mfma_f32_16x16x32_bf16 v[122:125], v[182:185], v[138:141], v[122:125]
	v_mfma_f32_16x16x32_bf16 v[118:121], v[186:189], v[138:141], v[118:121]
	v_mfma_f32_16x16x32_bf16 v[114:117], v[190:193], v[138:141], v[114:117]
	v_mfma_f32_16x16x32_bf16 v[110:113], v[178:181], v[150:153], v[110:113]
	v_mfma_f32_16x16x32_bf16 v[106:109], v[182:185], v[150:153], v[106:109]
	v_mfma_f32_16x16x32_bf16 v[102:105], v[186:189], v[150:153], v[102:105]
	v_mfma_f32_16x16x32_bf16 v[98:101], v[190:193], v[150:153], v[98:101]
	v_mfma_f32_16x16x32_bf16 v[94:97], v[178:181], v[154:157], v[94:97]
	v_mfma_f32_16x16x32_bf16 v[90:93], v[182:185], v[154:157], v[90:93]
	v_mfma_f32_16x16x32_bf16 v[86:89], v[186:189], v[154:157], v[86:89]
	v_mfma_f32_16x16x32_bf16 v[82:85], v[190:193], v[154:157], v[82:85]
	v_mfma_f32_16x16x32_bf16 v[78:81], v[178:181], v[158:161], v[78:81]
	v_mfma_f32_16x16x32_bf16 v[74:77], v[182:185], v[158:161], v[74:77]
	v_mfma_f32_16x16x32_bf16 v[70:73], v[186:189], v[158:161], v[70:73]
	v_mfma_f32_16x16x32_bf16 v[66:69], v[190:193], v[158:161], v[66:69]
	v_mfma_f32_16x16x32_bf16 v[62:65], v[178:181], v[162:165], v[62:65]
	v_mfma_f32_16x16x32_bf16 v[58:61], v[182:185], v[162:165], v[58:61]
	v_mfma_f32_16x16x32_bf16 v[54:57], v[186:189], v[162:165], v[54:57]
	v_mfma_f32_16x16x32_bf16 v[50:53], v[190:193], v[162:165], v[50:53]
	v_mfma_f32_16x16x32_bf16 v[46:49], v[178:181], v[166:169], v[46:49]
	v_mfma_f32_16x16x32_bf16 v[42:45], v[182:185], v[166:169], v[42:45]
	v_mfma_f32_16x16x32_bf16 v[38:41], v[186:189], v[166:169], v[38:41]
	v_mfma_f32_16x16x32_bf16 v[34:37], v[190:193], v[166:169], v[34:37]
	v_mfma_f32_16x16x32_bf16 v[30:33], v[178:181], v[170:173], v[30:33]
	v_mfma_f32_16x16x32_bf16 v[26:29], v[182:185], v[170:173], v[26:29]
	v_mfma_f32_16x16x32_bf16 v[22:25], v[186:189], v[170:173], v[22:25]
	v_mfma_f32_16x16x32_bf16 v[18:21], v[190:193], v[170:173], v[18:21]
	v_mfma_f32_16x16x32_bf16 v[14:17], v[178:181], v[174:177], v[14:17]
	v_mfma_f32_16x16x32_bf16 v[10:13], v[182:185], v[174:177], v[10:13]
	v_mfma_f32_16x16x32_bf16 v[6:9], v[186:189], v[174:177], v[6:9]
	v_mfma_f32_16x16x32_bf16 v[2:5], v[190:193], v[174:177], v[2:5]
	s_setprio 0
	v_add_u32_e32 v149, s26, v145
	v_or_b32_e32 v138, s38, v146
	s_waitcnt lgkmcnt(0)
	v_mov_b64_e32 v[140:141], s[80:81]
	v_ashrrev_i32_e32 v139, 31, v138
	v_cvt_pk_bf16_f32 v118, v118, v119
	v_cvt_pk_bf16_f32 v119, v120, v121
	v_cvt_pk_bf16_f32 v120, v114, v115
	v_or_b32_e32 v114, 16, v149
	v_cvt_pk_bf16_f32 v102, v102, v103
	v_cvt_pk_bf16_f32 v103, v104, v105
	v_cvt_pk_bf16_f32 v104, v98, v99
	v_or_b32_e32 v98, 32, v149
	v_cvt_pk_bf16_f32 v86, v86, v87
	v_cvt_pk_bf16_f32 v87, v88, v89
	v_cvt_pk_bf16_f32 v88, v82, v83
	v_or_b32_e32 v82, 48, v149
	v_cvt_pk_bf16_f32 v70, v70, v71
	v_cvt_pk_bf16_f32 v71, v72, v73
	v_cvt_pk_bf16_f32 v72, v66, v67
	v_or_b32_e32 v66, 64, v149
	v_cvt_pk_bf16_f32 v54, v54, v55
	v_cvt_pk_bf16_f32 v55, v56, v57
	v_cvt_pk_bf16_f32 v56, v50, v51
	v_or_b32_e32 v50, 0x50, v149
	v_cvt_pk_bf16_f32 v38, v38, v39
	v_cvt_pk_bf16_f32 v39, v40, v41
	v_cvt_pk_bf16_f32 v40, v34, v35
	v_or_b32_e32 v34, 0x60, v149
	v_cvt_pk_bf16_f32 v22, v22, v23
	v_cvt_pk_bf16_f32 v23, v24, v25
	v_cvt_pk_bf16_f32 v24, v18, v19
	v_or_b32_e32 v18, 0x70, v149
	v_mad_i64_i32 v[150:151], s[2:3], v149, s17, v[140:141]
	v_cvt_pk_bf16_f32 v126, v126, v127
	v_cvt_pk_bf16_f32 v127, v128, v129
	v_cvt_pk_bf16_f32 v128, v122, v123
	v_lshlrev_b64 v[122:123], 1, v[138:139]
	v_mad_i64_i32 v[114:115], s[2:3], v114, s17, v[140:141]
	v_mad_i64_i32 v[98:99], s[2:3], v98, s17, v[140:141]
	v_mad_i64_i32 v[82:83], s[2:3], v82, s17, v[140:141]
	v_mad_i64_i32 v[66:67], s[2:3], v66, s17, v[140:141]
	v_mad_i64_i32 v[50:51], s[2:3], v50, s17, v[140:141]
	v_mad_i64_i32 v[34:35], s[2:3], v34, s17, v[140:141]
	v_mad_i64_i32 v[18:19], s[2:3], v18, s17, v[140:141]
	v_cvt_pk_bf16_f32 v129, v124, v125
	v_lshl_add_u64 v[124:125], v[150:151], 0, v[122:123]
	v_cvt_pk_bf16_f32 v121, v116, v117
	v_cvt_pk_bf16_f32 v110, v110, v111
	v_cvt_pk_bf16_f32 v111, v112, v113
	v_cvt_pk_bf16_f32 v112, v106, v107
	v_cvt_pk_bf16_f32 v113, v108, v109
	v_lshl_add_u64 v[106:107], v[114:115], 0, v[122:123]
	v_cvt_pk_bf16_f32 v105, v100, v101
	v_cvt_pk_bf16_f32 v94, v94, v95
	v_cvt_pk_bf16_f32 v95, v96, v97
	v_cvt_pk_bf16_f32 v96, v90, v91
	v_cvt_pk_bf16_f32 v97, v92, v93
	v_lshl_add_u64 v[90:91], v[98:99], 0, v[122:123]
	v_cvt_pk_bf16_f32 v89, v84, v85
	v_cvt_pk_bf16_f32 v78, v78, v79
	v_cvt_pk_bf16_f32 v79, v80, v81
	v_cvt_pk_bf16_f32 v80, v74, v75
	v_cvt_pk_bf16_f32 v81, v76, v77
	v_lshl_add_u64 v[74:75], v[82:83], 0, v[122:123]
	v_cvt_pk_bf16_f32 v73, v68, v69
	v_cvt_pk_bf16_f32 v62, v62, v63
	v_cvt_pk_bf16_f32 v63, v64, v65
	v_cvt_pk_bf16_f32 v64, v58, v59
	v_cvt_pk_bf16_f32 v65, v60, v61
	v_lshl_add_u64 v[58:59], v[66:67], 0, v[122:123]
	v_cvt_pk_bf16_f32 v57, v52, v53
	v_cvt_pk_bf16_f32 v46, v46, v47
	v_cvt_pk_bf16_f32 v47, v48, v49
	v_cvt_pk_bf16_f32 v48, v42, v43
	v_cvt_pk_bf16_f32 v49, v44, v45
	v_lshl_add_u64 v[42:43], v[50:51], 0, v[122:123]
	v_cvt_pk_bf16_f32 v41, v36, v37
	v_cvt_pk_bf16_f32 v30, v30, v31
	v_cvt_pk_bf16_f32 v31, v32, v33
	v_cvt_pk_bf16_f32 v32, v26, v27
	v_cvt_pk_bf16_f32 v33, v28, v29
	v_lshl_add_u64 v[26:27], v[34:35], 0, v[122:123]
	v_cvt_pk_bf16_f32 v25, v20, v21
	v_cvt_pk_bf16_f32 v14, v14, v15
	v_cvt_pk_bf16_f32 v15, v16, v17
	v_cvt_pk_bf16_f32 v16, v10, v11
	v_cvt_pk_bf16_f32 v17, v12, v13
	v_lshl_add_u64 v[10:11], v[18:19], 0, v[122:123]
	v_cvt_pk_bf16_f32 v6, v6, v7
	v_cvt_pk_bf16_f32 v7, v8, v9
	v_cvt_pk_bf16_f32 v8, v2, v3
	v_cvt_pk_bf16_f32 v9, v4, v5
	s_movk_i32 s38, 0xff
	s_barrier
	global_store_dwordx4 v[124:125], v[126:129], off
	global_store_dwordx4 v[124:125], v[118:121], off offset:64
	global_store_dwordx4 v[106:107], v[110:113], off
	global_store_dwordx4 v[106:107], v[102:105], off offset:64
	global_store_dwordx4 v[90:91], v[94:97], off
	global_store_dwordx4 v[90:91], v[86:89], off offset:64
	global_store_dwordx4 v[74:75], v[78:81], off
	global_store_dwordx4 v[74:75], v[70:73], off offset:64
	global_store_dwordx4 v[58:59], v[62:65], off
	global_store_dwordx4 v[58:59], v[54:57], off offset:64
	global_store_dwordx4 v[42:43], v[46:49], off
	global_store_dwordx4 v[42:43], v[38:41], off offset:64
	global_store_dwordx4 v[26:27], v[30:33], off
	global_store_dwordx4 v[26:27], v[22:25], off offset:64
	global_store_dwordx4 v[10:11], v[14:17], off
	global_store_dwordx4 v[10:11], v[6:9], off offset:64
	s_branch .LBB0_184

.LBB0_1143:
	s_mul_i32 s13, s12, 0x6000
	s_add_i32 s13, s13, 0
	s_waitcnt vmcnt(6)
	v_add3_u32 v149, s13, v143, v142
	s_waitcnt lgkmcnt(0)
	s_barrier
	v_add3_u32 v248, s13, v144, v142
	ds_read_b128 v[182:185], v248 offset:16384
	ds_read_b128 v[186:189], v248 offset:17408
	ds_read_b128 v[190:193], v248 offset:18432
	ds_read_b128 v[194:197], v248 offset:19456
	ds_read_b128 v[150:153], v149
	ds_read_b128 v[154:157], v149 offset:1024
	ds_read_b128 v[158:161], v149 offset:2048
	ds_read_b128 v[162:165], v149 offset:3072
	ds_read_b128 v[166:169], v149 offset:4096
	ds_read_b128 v[170:173], v149 offset:5120
	ds_read_b128 v[174:177], v149 offset:6144
	ds_read_b128 v[178:181], v149 offset:7168
	s_cmp_gt_i32 s12, 0
	s_cselect_b32 s13, -1, 2
	s_add_i32 s13, s13, s12
	s_mulk_i32 s13, 0x6000
	v_lshl_add_u64 v[198:199], v[140:141], 0, s[6:7]
	s_add_i32 s13, s11, s13
	v_lshl_add_u64 v[200:201], v[198:199], 0, s[28:29]
	s_mov_b32 m0, s13
	s_mov_b64 s[14:15], 0x1b30080
	global_load_lds_dwordx4 v[200:201], off
	v_lshl_add_u64 v[200:201], v[198:199], 0, s[30:31]
	s_add_i32 m0, s13, 0x1000
	s_nop 0
	global_load_lds_dwordx4 v[200:201], off
	v_lshl_add_u64 v[200:201], v[198:199], 0, s[34:35]
	s_add_i32 m0, s13, 0x2000
	v_lshl_add_u64 v[198:199], v[198:199], 0, s[42:43]
	global_load_lds_dwordx4 v[200:201], off
	s_add_i32 m0, s13, 0x3000
	s_nop 0
	global_load_lds_dwordx4 v[198:199], off
	v_lshl_add_u64 v[198:199], v[138:139], 0, s[6:7]
	v_lshl_add_u64 v[200:201], v[198:199], 0, s[14:15]
	s_add_i32 m0, s13, 0x4000
	s_mov_b64 s[14:15], 0x1b50080
	global_load_lds_dwordx4 v[200:201], off
	v_lshl_add_u64 v[198:199], v[198:199], 0, s[14:15]
	s_add_i32 m0, s13, 0x5000
	s_nop 0
	global_load_lds_dwordx4 v[198:199], off
	s_setprio 1
	s_waitcnt lgkmcnt(7)
	v_mfma_f32_16x16x32_bf16 v[126:129], v[182:185], v[150:153], v[126:129]
	v_mfma_f32_16x16x32_bf16 v[122:125], v[186:189], v[150:153], v[122:125]
	v_mfma_f32_16x16x32_bf16 v[118:121], v[190:193], v[150:153], v[118:121]
	v_mfma_f32_16x16x32_bf16 v[114:117], v[194:197], v[150:153], v[114:117]
	s_waitcnt lgkmcnt(6)
	v_mfma_f32_16x16x32_bf16 v[110:113], v[182:185], v[154:157], v[110:113]
	v_mfma_f32_16x16x32_bf16 v[106:109], v[186:189], v[154:157], v[106:109]
	v_mfma_f32_16x16x32_bf16 v[102:105], v[190:193], v[154:157], v[102:105]
	v_mfma_f32_16x16x32_bf16 v[98:101], v[194:197], v[154:157], v[98:101]
	s_waitcnt lgkmcnt(5)
	v_mfma_f32_16x16x32_bf16 v[94:97], v[182:185], v[158:161], v[94:97]
	v_mfma_f32_16x16x32_bf16 v[90:93], v[186:189], v[158:161], v[90:93]
	v_mfma_f32_16x16x32_bf16 v[86:89], v[190:193], v[158:161], v[86:89]
	v_mfma_f32_16x16x32_bf16 v[82:85], v[194:197], v[158:161], v[82:85]
	s_waitcnt lgkmcnt(4)
	v_mfma_f32_16x16x32_bf16 v[78:81], v[182:185], v[162:165], v[78:81]
	v_mfma_f32_16x16x32_bf16 v[74:77], v[186:189], v[162:165], v[74:77]
	v_mfma_f32_16x16x32_bf16 v[70:73], v[190:193], v[162:165], v[70:73]
	v_mfma_f32_16x16x32_bf16 v[66:69], v[194:197], v[162:165], v[66:69]
	s_waitcnt lgkmcnt(3)
	v_mfma_f32_16x16x32_bf16 v[62:65], v[182:185], v[166:169], v[62:65]
	v_mfma_f32_16x16x32_bf16 v[58:61], v[186:189], v[166:169], v[58:61]
	v_mfma_f32_16x16x32_bf16 v[54:57], v[190:193], v[166:169], v[54:57]
	v_mfma_f32_16x16x32_bf16 v[50:53], v[194:197], v[166:169], v[50:53]
	s_waitcnt lgkmcnt(2)
	v_mfma_f32_16x16x32_bf16 v[46:49], v[182:185], v[170:173], v[46:49]
	v_mfma_f32_16x16x32_bf16 v[42:45], v[186:189], v[170:173], v[42:45]
	v_mfma_f32_16x16x32_bf16 v[38:41], v[190:193], v[170:173], v[38:41]
	v_mfma_f32_16x16x32_bf16 v[34:37], v[194:197], v[170:173], v[34:37]
	s_waitcnt lgkmcnt(1)
	v_mfma_f32_16x16x32_bf16 v[30:33], v[182:185], v[174:177], v[30:33]
	v_mfma_f32_16x16x32_bf16 v[26:29], v[186:189], v[174:177], v[26:29]
	v_mfma_f32_16x16x32_bf16 v[22:25], v[190:193], v[174:177], v[22:25]
	v_mfma_f32_16x16x32_bf16 v[18:21], v[194:197], v[174:177], v[18:21]
	s_waitcnt lgkmcnt(0)
	v_mfma_f32_16x16x32_bf16 v[14:17], v[182:185], v[178:181], v[14:17]
	v_mfma_f32_16x16x32_bf16 v[10:13], v[186:189], v[178:181], v[10:13]
	v_mfma_f32_16x16x32_bf16 v[6:9], v[190:193], v[178:181], v[6:9]
	v_mfma_f32_16x16x32_bf16 v[2:5], v[194:197], v[178:181], v[2:5]
	s_setprio 0
	s_add_i32 s12, s12, 1
	s_cmp_lg_u32 s12, 3
	s_cselect_b32 s12, s12, 0
	s_add_u32 s6, s6, 64
	s_addc_u32 s7, s7, 0
	s_cmpk_lg_i32 s6, 0x780
	s_cbranch_scc1 .LBB0_1143
	s_waitcnt vmcnt(6)
	s_waitcnt lgkmcnt(0)
	s_barrier
	ds_read_b128 v[138:141], v147
	ds_read_b128 v[150:153], v147 offset:1024
	ds_read_b128 v[154:157], v147 offset:2048
	ds_read_b128 v[158:161], v147 offset:3072
	ds_read_b128 v[162:165], v147 offset:4096
	ds_read_b128 v[166:169], v147 offset:5120
	ds_read_b128 v[170:173], v147 offset:6144
	ds_read_b128 v[174:177], v147 offset:7168
	ds_read_b128 v[178:181], v148 offset:16384
	ds_read_b128 v[182:185], v148 offset:17408
	ds_read_b128 v[186:189], v148 offset:18432
	ds_read_b128 v[190:193], v148 offset:19456
	s_setprio 1
	s_waitcnt lgkmcnt(0)
	v_mfma_f32_16x16x32_bf16 v[126:129], v[178:181], v[138:141], v[126:129]
	v_mfma_f32_16x16x32_bf16 v[122:125], v[182:185], v[138:141], v[122:125]
	v_mfma_f32_16x16x32_bf16 v[118:121], v[186:189], v[138:141], v[118:121]
	v_mfma_f32_16x16x32_bf16 v[114:117], v[190:193], v[138:141], v[114:117]
	v_mfma_f32_16x16x32_bf16 v[110:113], v[178:181], v[150:153], v[110:113]
	v_mfma_f32_16x16x32_bf16 v[106:109], v[182:185], v[150:153], v[106:109]
	v_mfma_f32_16x16x32_bf16 v[102:105], v[186:189], v[150:153], v[102:105]
	v_mfma_f32_16x16x32_bf16 v[98:101], v[190:193], v[150:153], v[98:101]
	v_mfma_f32_16x16x32_bf16 v[94:97], v[178:181], v[154:157], v[94:97]
	v_mfma_f32_16x16x32_bf16 v[90:93], v[182:185], v[154:157], v[90:93]
	v_mfma_f32_16x16x32_bf16 v[86:89], v[186:189], v[154:157], v[86:89]
	v_mfma_f32_16x16x32_bf16 v[82:85], v[190:193], v[154:157], v[82:85]
	v_mfma_f32_16x16x32_bf16 v[78:81], v[178:181], v[158:161], v[78:81]
	v_mfma_f32_16x16x32_bf16 v[74:77], v[182:185], v[158:161], v[74:77]
	v_mfma_f32_16x16x32_bf16 v[70:73], v[186:189], v[158:161], v[70:73]
	v_mfma_f32_16x16x32_bf16 v[66:69], v[190:193], v[158:161], v[66:69]
	v_mfma_f32_16x16x32_bf16 v[62:65], v[178:181], v[162:165], v[62:65]
	v_mfma_f32_16x16x32_bf16 v[58:61], v[182:185], v[162:165], v[58:61]
	v_mfma_f32_16x16x32_bf16 v[54:57], v[186:189], v[162:165], v[54:57]
	v_mfma_f32_16x16x32_bf16 v[50:53], v[190:193], v[162:165], v[50:53]
	v_mfma_f32_16x16x32_bf16 v[46:49], v[178:181], v[166:169], v[46:49]
	v_mfma_f32_16x16x32_bf16 v[42:45], v[182:185], v[166:169], v[42:45]
	v_mfma_f32_16x16x32_bf16 v[38:41], v[186:189], v[166:169], v[38:41]
	v_mfma_f32_16x16x32_bf16 v[34:37], v[190:193], v[166:169], v[34:37]
	v_mfma_f32_16x16x32_bf16 v[30:33], v[178:181], v[170:173], v[30:33]
	v_mfma_f32_16x16x32_bf16 v[26:29], v[182:185], v[170:173], v[26:29]
	v_mfma_f32_16x16x32_bf16 v[22:25], v[186:189], v[170:173], v[22:25]
	v_mfma_f32_16x16x32_bf16 v[18:21], v[190:193], v[170:173], v[18:21]
	v_mfma_f32_16x16x32_bf16 v[14:17], v[178:181], v[174:177], v[14:17]
	v_mfma_f32_16x16x32_bf16 v[10:13], v[182:185], v[174:177], v[10:13]
	v_mfma_f32_16x16x32_bf16 v[6:9], v[186:189], v[174:177], v[6:9]
	v_mfma_f32_16x16x32_bf16 v[2:5], v[190:193], v[174:177], v[2:5]
	s_setprio 0
	s_waitcnt vmcnt(0)
	s_waitcnt lgkmcnt(0)
	s_barrier
	ds_read_b128 v[138:141], v147 offset:24576
	ds_read_b128 v[150:153], v147 offset:25600
	ds_read_b128 v[154:157], v147 offset:26624
	ds_read_b128 v[158:161], v147 offset:27648
	ds_read_b128 v[162:165], v147 offset:28672
	ds_read_b128 v[166:169], v147 offset:29696
	ds_read_b128 v[170:173], v147 offset:30720
	ds_read_b128 v[174:177], v147 offset:31744
	ds_read_b128 v[178:181], v148 offset:40960
	ds_read_b128 v[182:185], v148 offset:41984
	ds_read_b128 v[186:189], v148 offset:43008
	ds_read_b128 v[190:193], v148 offset:44032
	s_setprio 1
	s_waitcnt lgkmcnt(0)
	v_mfma_f32_16x16x32_bf16 v[126:129], v[178:181], v[138:141], v[126:129]
	v_mfma_f32_16x16x32_bf16 v[122:125], v[182:185], v[138:141], v[122:125]
	v_mfma_f32_16x16x32_bf16 v[118:121], v[186:189], v[138:141], v[118:121]
	v_mfma_f32_16x16x32_bf16 v[114:117], v[190:193], v[138:141], v[114:117]
	v_mfma_f32_16x16x32_bf16 v[110:113], v[178:181], v[150:153], v[110:113]
	v_mfma_f32_16x16x32_bf16 v[106:109], v[182:185], v[150:153], v[106:109]
	v_mfma_f32_16x16x32_bf16 v[102:105], v[186:189], v[150:153], v[102:105]
	v_mfma_f32_16x16x32_bf16 v[98:101], v[190:193], v[150:153], v[98:101]
	v_mfma_f32_16x16x32_bf16 v[94:97], v[178:181], v[154:157], v[94:97]
	v_mfma_f32_16x16x32_bf16 v[90:93], v[182:185], v[154:157], v[90:93]
	v_mfma_f32_16x16x32_bf16 v[86:89], v[186:189], v[154:157], v[86:89]
	v_mfma_f32_16x16x32_bf16 v[138:141], v[190:193], v[154:157], v[82:85]
	v_mfma_f32_16x16x32_bf16 v[78:81], v[178:181], v[158:161], v[78:81]
	v_mfma_f32_16x16x32_bf16 v[74:77], v[182:185], v[158:161], v[74:77]
	v_mfma_f32_16x16x32_bf16 v[70:73], v[186:189], v[158:161], v[70:73]
	v_mfma_f32_16x16x32_bf16 v[66:69], v[190:193], v[158:161], v[66:69]
	v_mfma_f32_16x16x32_bf16 v[62:65], v[178:181], v[162:165], v[62:65]
	v_mfma_f32_16x16x32_bf16 v[58:61], v[182:185], v[162:165], v[58:61]
	v_mfma_f32_16x16x32_bf16 v[54:57], v[186:189], v[162:165], v[54:57]
	v_mfma_f32_16x16x32_bf16 v[50:53], v[190:193], v[162:165], v[50:53]
	v_mfma_f32_16x16x32_bf16 v[46:49], v[178:181], v[166:169], v[46:49]
	v_mfma_f32_16x16x32_bf16 v[42:45], v[182:185], v[166:169], v[42:45]
	v_mfma_f32_16x16x32_bf16 v[38:41], v[186:189], v[166:169], v[38:41]
	v_mfma_f32_16x16x32_bf16 v[34:37], v[190:193], v[166:169], v[34:37]
	v_mfma_f32_16x16x32_bf16 v[30:33], v[178:181], v[170:173], v[30:33]
	v_mfma_f32_16x16x32_bf16 v[26:29], v[182:185], v[170:173], v[26:29]
	v_mfma_f32_16x16x32_bf16 v[22:25], v[186:189], v[170:173], v[22:25]
	v_mfma_f32_16x16x32_bf16 v[18:21], v[190:193], v[170:173], v[18:21]
	v_mfma_f32_16x16x32_bf16 v[14:17], v[178:181], v[174:177], v[14:17]
	v_mfma_f32_16x16x32_bf16 v[10:13], v[182:185], v[174:177], v[10:13]
	v_mfma_f32_16x16x32_bf16 v[6:9], v[186:189], v[174:177], v[6:9]
	v_mfma_f32_16x16x32_bf16 v[2:5], v[190:193], v[174:177], v[2:5]
	s_setprio 0
	v_add_u32_e32 v82, s26, v145
	v_ashrrev_i32_e32 v83, 31, v82
	v_lshlrev_b64 v[150:151], 13, v[82:83]
	v_max_f32_e32 v83, v126, v126
	v_max_f32_e32 v126, 0, v83
	v_max_f32_e32 v83, v122, v122
	v_max_f32_e32 v152, 0, v83
	v_max_f32_e32 v83, v127, v127
	v_max_f32_e32 v127, 0, v83
	v_max_f32_e32 v83, v123, v123
	v_max_f32_e32 v153, 0, v83
	v_max_f32_e32 v83, v128, v128
	v_max_f32_e32 v128, 0, v83
	v_max_f32_e32 v83, v124, v124
	v_max_f32_e32 v154, 0, v83
	v_max_f32_e32 v83, v129, v129
	v_or_b32_e32 v84, s38, v146
	v_max_f32_e32 v129, 0, v83
	v_max_f32_e32 v83, v125, v125
	v_max_f32_e32 v155, 0, v83
	v_pk_mul_f32 v[122:123], v[126:127], v[126:127]
	v_pk_mul_f32 v[124:125], v[128:129], v[128:129]
	v_ashrrev_i32_e32 v85, 31, v84
	v_lshl_add_u64 v[150:151], s[80:81], 0, v[150:151]
	v_cvt_pk_bf16_f32 v122, v122, v123
	v_cvt_pk_bf16_f32 v123, v124, v125
	v_pk_mul_f32 v[124:125], v[152:153], v[152:153]
	v_pk_mul_f32 v[126:127], v[154:155], v[154:155]
	v_lshlrev_b64 v[84:85], 1, v[84:85]
	v_max_f32_e32 v83, v118, v118
	v_cvt_pk_bf16_f32 v124, v124, v125
	v_cvt_pk_bf16_f32 v125, v126, v127
	v_lshl_add_u64 v[126:127], v[150:151], 0, v[84:85]
	v_max_f32_e32 v118, 0, v83
	v_max_f32_e32 v83, v114, v114
	s_waitcnt lgkmcnt(0)
	s_barrier
	global_store_dwordx4 v[126:127], v[122:125], off
	v_max_f32_e32 v74, v74, v74
	v_max_f32_e32 v78, v78, v78
	v_max_f32_e32 v122, 0, v83
	v_max_f32_e32 v83, v119, v119
	v_max_f32_e32 v119, 0, v83
	v_max_f32_e32 v83, v115, v115
	v_max_f32_e32 v123, 0, v83
	v_max_f32_e32 v83, v120, v120
	v_max_f32_e32 v120, 0, v83
	v_max_f32_e32 v83, v116, v116
	v_max_f32_e32 v124, 0, v83
	v_max_f32_e32 v83, v121, v121
	v_max_f32_e32 v121, 0, v83
	v_max_f32_e32 v83, v117, v117
	v_max_f32_e32 v125, 0, v83
	v_pk_mul_f32 v[114:115], v[118:119], v[118:119]
	v_pk_mul_f32 v[116:117], v[120:121], v[120:121]
	v_cvt_pk_bf16_f32 v114, v114, v115
	v_cvt_pk_bf16_f32 v115, v116, v117
	v_pk_mul_f32 v[116:117], v[122:123], v[122:123]
	v_pk_mul_f32 v[118:119], v[124:125], v[124:125]
	v_max_f32_e32 v83, v110, v110
	v_cvt_pk_bf16_f32 v116, v116, v117
	v_cvt_pk_bf16_f32 v117, v118, v119
	v_max_f32_e32 v110, 0, v83
	v_max_f32_e32 v83, v106, v106
	global_store_dwordx4 v[126:127], v[114:117], off offset:64
	v_max_f32_e32 v78, 0, v78
	v_max_f32_e32 v66, v66, v66
	v_max_f32_e32 v116, 0, v83
	v_max_f32_e32 v83, v111, v111
	v_max_f32_e32 v111, 0, v83
	v_max_f32_e32 v83, v107, v107
	v_max_f32_e32 v117, 0, v83
	v_max_f32_e32 v83, v112, v112
	v_max_f32_e32 v112, 0, v83
	v_max_f32_e32 v83, v108, v108
	v_or_b32_e32 v114, 16, v82
	v_max_f32_e32 v118, 0, v83
	v_max_f32_e32 v83, v113, v113
	v_ashrrev_i32_e32 v115, 31, v114
	v_max_f32_e32 v113, 0, v83
	v_max_f32_e32 v83, v109, v109
	v_lshlrev_b64 v[114:115], 13, v[114:115]
	v_max_f32_e32 v119, 0, v83
	v_pk_mul_f32 v[106:107], v[110:111], v[110:111]
	v_pk_mul_f32 v[108:109], v[112:113], v[112:113]
	v_lshl_add_u64 v[114:115], s[80:81], 0, v[114:115]
	v_cvt_pk_bf16_f32 v106, v106, v107
	v_cvt_pk_bf16_f32 v107, v108, v109
	v_pk_mul_f32 v[108:109], v[116:117], v[116:117]
	v_pk_mul_f32 v[110:111], v[118:119], v[118:119]
	v_max_f32_e32 v83, v102, v102
	v_cvt_pk_bf16_f32 v108, v108, v109
	v_cvt_pk_bf16_f32 v109, v110, v111
	v_lshl_add_u64 v[110:111], v[114:115], 0, v[84:85]
	v_max_f32_e32 v102, 0, v83
	v_max_f32_e32 v83, v98, v98
	global_store_dwordx4 v[110:111], v[106:109], off
	v_max_f32_e32 v70, v70, v70
	v_max_f32_e32 v70, 0, v70
	v_max_f32_e32 v106, 0, v83
	v_max_f32_e32 v83, v103, v103
	v_max_f32_e32 v103, 0, v83
	v_max_f32_e32 v83, v99, v99
	v_max_f32_e32 v107, 0, v83
	v_max_f32_e32 v83, v104, v104
	v_max_f32_e32 v104, 0, v83
	v_max_f32_e32 v83, v100, v100
	v_max_f32_e32 v108, 0, v83
	v_max_f32_e32 v83, v105, v105
	v_max_f32_e32 v105, 0, v83
	v_max_f32_e32 v83, v101, v101
	v_max_f32_e32 v109, 0, v83
	v_pk_mul_f32 v[98:99], v[102:103], v[102:103]
	v_pk_mul_f32 v[100:101], v[104:105], v[104:105]
	v_cvt_pk_bf16_f32 v98, v98, v99
	v_cvt_pk_bf16_f32 v99, v100, v101
	v_pk_mul_f32 v[100:101], v[106:107], v[106:107]
	v_pk_mul_f32 v[102:103], v[108:109], v[108:109]
	v_max_f32_e32 v83, v94, v94
	v_cvt_pk_bf16_f32 v100, v100, v101
	v_cvt_pk_bf16_f32 v101, v102, v103
	v_max_f32_e32 v94, 0, v83
	v_max_f32_e32 v83, v90, v90
	global_store_dwordx4 v[110:111], v[98:101], off offset:64
	v_max_f32_e32 v58, v58, v58
	v_max_f32_e32 v62, v62, v62
	v_max_f32_e32 v100, 0, v83
	v_max_f32_e32 v83, v95, v95
	v_max_f32_e32 v95, 0, v83
	v_max_f32_e32 v83, v91, v91
	v_max_f32_e32 v101, 0, v83
	v_max_f32_e32 v83, v96, v96
	v_max_f32_e32 v96, 0, v83
	v_max_f32_e32 v83, v92, v92
	v_or_b32_e32 v98, 32, v82
	v_max_f32_e32 v102, 0, v83
	v_max_f32_e32 v83, v97, v97
	v_ashrrev_i32_e32 v99, 31, v98
	v_max_f32_e32 v97, 0, v83
	v_max_f32_e32 v83, v93, v93
	v_lshlrev_b64 v[98:99], 13, v[98:99]
	v_max_f32_e32 v103, 0, v83
	v_pk_mul_f32 v[90:91], v[94:95], v[94:95]
	v_pk_mul_f32 v[92:93], v[96:97], v[96:97]
	v_lshl_add_u64 v[98:99], s[80:81], 0, v[98:99]
	v_cvt_pk_bf16_f32 v90, v90, v91
	v_cvt_pk_bf16_f32 v91, v92, v93
	v_pk_mul_f32 v[92:93], v[100:101], v[100:101]
	v_pk_mul_f32 v[94:95], v[102:103], v[102:103]
	v_max_f32_e32 v83, v86, v86
	v_cvt_pk_bf16_f32 v92, v92, v93
	v_cvt_pk_bf16_f32 v93, v94, v95
	v_lshl_add_u64 v[94:95], v[98:99], 0, v[84:85]
	v_max_f32_e32 v86, 0, v83
	v_max_f32_e32 v83, v138, v138
	global_store_dwordx4 v[94:95], v[90:93], off
	v_max_f32_e32 v62, 0, v62
	v_max_f32_e32 v50, v50, v50
	v_max_f32_e32 v90, 0, v83
	v_max_f32_e32 v83, v87, v87
	v_max_f32_e32 v87, 0, v83
	v_max_f32_e32 v83, v139, v139
	v_max_f32_e32 v91, 0, v83
	v_max_f32_e32 v83, v88, v88
	v_max_f32_e32 v88, 0, v83
	v_max_f32_e32 v83, v140, v140
	v_max_f32_e32 v92, 0, v83
	v_max_f32_e32 v83, v89, v89
	v_max_f32_e32 v89, 0, v83
	v_max_f32_e32 v83, v141, v141
	v_max_f32_e32 v93, 0, v83
	v_pk_mul_f32 v[86:87], v[86:87], v[86:87]
	v_pk_mul_f32 v[88:89], v[88:89], v[88:89]
	v_cvt_pk_bf16_f32 v86, v86, v87
	v_cvt_pk_bf16_f32 v87, v88, v89
	v_pk_mul_f32 v[88:89], v[90:91], v[90:91]
	v_pk_mul_f32 v[90:91], v[92:93], v[92:93]
	v_cvt_pk_bf16_f32 v88, v88, v89
	v_cvt_pk_bf16_f32 v89, v90, v91
	global_store_dwordx4 v[94:95], v[86:89], off offset:64
	v_max_f32_e32 v54, v54, v54
	v_max_f32_e32 v54, 0, v54
	v_max_f32_e32 v88, 0, v74
	v_max_f32_e32 v74, v79, v79
	v_max_f32_e32 v79, 0, v74
	v_max_f32_e32 v74, v75, v75
	v_max_f32_e32 v89, 0, v74
	v_max_f32_e32 v74, v80, v80
	v_max_f32_e32 v80, 0, v74
	v_max_f32_e32 v74, v76, v76
	v_or_b32_e32 v86, 48, v82
	v_max_f32_e32 v90, 0, v74
	v_max_f32_e32 v74, v81, v81
	v_ashrrev_i32_e32 v87, 31, v86
	v_max_f32_e32 v81, 0, v74
	v_max_f32_e32 v74, v77, v77
	v_lshlrev_b64 v[86:87], 13, v[86:87]
	v_max_f32_e32 v91, 0, v74
	v_pk_mul_f32 v[74:75], v[78:79], v[78:79]
	v_pk_mul_f32 v[76:77], v[80:81], v[80:81]
	v_lshl_add_u64 v[86:87], s[80:81], 0, v[86:87]
	v_cvt_pk_bf16_f32 v74, v74, v75
	v_cvt_pk_bf16_f32 v75, v76, v77
	v_pk_mul_f32 v[76:77], v[88:89], v[88:89]
	v_pk_mul_f32 v[78:79], v[90:91], v[90:91]
	v_cvt_pk_bf16_f32 v76, v76, v77
	v_cvt_pk_bf16_f32 v77, v78, v79
	v_lshl_add_u64 v[78:79], v[86:87], 0, v[84:85]
	global_store_dwordx4 v[78:79], v[74:77], off
	v_max_f32_e32 v42, v42, v42
	v_max_f32_e32 v46, v46, v46
	v_max_f32_e32 v74, 0, v66
	v_max_f32_e32 v66, v71, v71
	v_max_f32_e32 v71, 0, v66
	v_max_f32_e32 v66, v67, v67
	v_max_f32_e32 v75, 0, v66
	v_max_f32_e32 v66, v72, v72
	v_max_f32_e32 v72, 0, v66
	v_max_f32_e32 v66, v68, v68
	v_max_f32_e32 v76, 0, v66
	v_max_f32_e32 v66, v73, v73
	v_max_f32_e32 v73, 0, v66
	v_max_f32_e32 v66, v69, v69
	v_max_f32_e32 v77, 0, v66
	v_pk_mul_f32 v[66:67], v[70:71], v[70:71]
	v_pk_mul_f32 v[68:69], v[72:73], v[72:73]
	v_cvt_pk_bf16_f32 v66, v66, v67
	v_cvt_pk_bf16_f32 v67, v68, v69
	v_pk_mul_f32 v[68:69], v[74:75], v[74:75]
	v_pk_mul_f32 v[70:71], v[76:77], v[76:77]
	v_cvt_pk_bf16_f32 v68, v68, v69
	v_cvt_pk_bf16_f32 v69, v70, v71
	global_store_dwordx4 v[78:79], v[66:69], off offset:64
	v_max_f32_e32 v46, 0, v46
	v_max_f32_e32 v34, v34, v34
	v_max_f32_e32 v68, 0, v58
	v_max_f32_e32 v58, v63, v63
	v_max_f32_e32 v63, 0, v58
	v_max_f32_e32 v58, v59, v59
	v_max_f32_e32 v69, 0, v58
	v_max_f32_e32 v58, v64, v64
	v_max_f32_e32 v64, 0, v58
	v_max_f32_e32 v58, v60, v60
	v_or_b32_e32 v66, 64, v82
	v_max_f32_e32 v70, 0, v58
	v_max_f32_e32 v58, v65, v65
	v_ashrrev_i32_e32 v67, 31, v66
	v_max_f32_e32 v65, 0, v58
	v_max_f32_e32 v58, v61, v61
	v_lshlrev_b64 v[66:67], 13, v[66:67]
	v_max_f32_e32 v71, 0, v58
	v_pk_mul_f32 v[58:59], v[62:63], v[62:63]
	v_pk_mul_f32 v[60:61], v[64:65], v[64:65]
	v_lshl_add_u64 v[66:67], s[80:81], 0, v[66:67]
	v_cvt_pk_bf16_f32 v58, v58, v59
	v_cvt_pk_bf16_f32 v59, v60, v61
	v_pk_mul_f32 v[60:61], v[68:69], v[68:69]
	v_pk_mul_f32 v[62:63], v[70:71], v[70:71]
	v_cvt_pk_bf16_f32 v60, v60, v61
	v_cvt_pk_bf16_f32 v61, v62, v63
	v_lshl_add_u64 v[62:63], v[66:67], 0, v[84:85]
	global_store_dwordx4 v[62:63], v[58:61], off
	v_max_f32_e32 v38, v38, v38
	v_max_f32_e32 v38, 0, v38
	v_max_f32_e32 v58, 0, v50
	v_max_f32_e32 v50, v55, v55
	v_max_f32_e32 v55, 0, v50
	v_max_f32_e32 v50, v51, v51
	v_max_f32_e32 v59, 0, v50
	v_max_f32_e32 v50, v56, v56
	v_max_f32_e32 v56, 0, v50
	v_max_f32_e32 v50, v52, v52
	v_max_f32_e32 v60, 0, v50
	v_max_f32_e32 v50, v57, v57
	v_max_f32_e32 v57, 0, v50
	v_max_f32_e32 v50, v53, v53
	v_max_f32_e32 v61, 0, v50
	v_pk_mul_f32 v[50:51], v[54:55], v[54:55]
	v_pk_mul_f32 v[52:53], v[56:57], v[56:57]
	v_cvt_pk_bf16_f32 v50, v50, v51
	v_cvt_pk_bf16_f32 v51, v52, v53
	v_pk_mul_f32 v[52:53], v[58:59], v[58:59]
	v_pk_mul_f32 v[54:55], v[60:61], v[60:61]
	v_cvt_pk_bf16_f32 v52, v52, v53
	v_cvt_pk_bf16_f32 v53, v54, v55
	global_store_dwordx4 v[62:63], v[50:53], off offset:64
	v_max_f32_e32 v26, v26, v26
	v_max_f32_e32 v30, v30, v30
	v_max_f32_e32 v52, 0, v42
	v_max_f32_e32 v42, v47, v47
	v_max_f32_e32 v47, 0, v42
	v_max_f32_e32 v42, v43, v43
	v_max_f32_e32 v53, 0, v42
	v_max_f32_e32 v42, v48, v48
	v_max_f32_e32 v48, 0, v42
	v_max_f32_e32 v42, v44, v44
	v_or_b32_e32 v50, 0x50, v82
	v_max_f32_e32 v54, 0, v42
	v_max_f32_e32 v42, v49, v49
	v_ashrrev_i32_e32 v51, 31, v50
	v_max_f32_e32 v49, 0, v42
	v_max_f32_e32 v42, v45, v45
	v_lshlrev_b64 v[50:51], 13, v[50:51]
	v_max_f32_e32 v55, 0, v42
	v_pk_mul_f32 v[42:43], v[46:47], v[46:47]
	v_pk_mul_f32 v[44:45], v[48:49], v[48:49]
	v_lshl_add_u64 v[50:51], s[80:81], 0, v[50:51]
	v_cvt_pk_bf16_f32 v42, v42, v43
	v_cvt_pk_bf16_f32 v43, v44, v45
	v_pk_mul_f32 v[44:45], v[52:53], v[52:53]
	v_pk_mul_f32 v[46:47], v[54:55], v[54:55]
	v_cvt_pk_bf16_f32 v44, v44, v45
	v_cvt_pk_bf16_f32 v45, v46, v47
	v_lshl_add_u64 v[46:47], v[50:51], 0, v[84:85]
	global_store_dwordx4 v[46:47], v[42:45], off
	v_max_f32_e32 v30, 0, v30
	v_max_f32_e32 v18, v18, v18
	v_max_f32_e32 v42, 0, v34
	v_max_f32_e32 v34, v39, v39
	v_max_f32_e32 v39, 0, v34
	v_max_f32_e32 v34, v35, v35
	v_max_f32_e32 v43, 0, v34
	v_max_f32_e32 v34, v40, v40
	v_max_f32_e32 v40, 0, v34
	v_max_f32_e32 v34, v36, v36
	v_max_f32_e32 v44, 0, v34
	v_max_f32_e32 v34, v41, v41
	v_max_f32_e32 v41, 0, v34
	v_max_f32_e32 v34, v37, v37
	v_max_f32_e32 v45, 0, v34
	v_pk_mul_f32 v[34:35], v[38:39], v[38:39]
	v_pk_mul_f32 v[36:37], v[40:41], v[40:41]
	v_cvt_pk_bf16_f32 v34, v34, v35
	v_cvt_pk_bf16_f32 v35, v36, v37
	v_pk_mul_f32 v[36:37], v[42:43], v[42:43]
	v_pk_mul_f32 v[38:39], v[44:45], v[44:45]
	v_cvt_pk_bf16_f32 v36, v36, v37
	v_cvt_pk_bf16_f32 v37, v38, v39
	global_store_dwordx4 v[46:47], v[34:37], off offset:64
	v_max_f32_e32 v22, v22, v22
	v_max_f32_e32 v22, 0, v22
	v_max_f32_e32 v36, 0, v26
	v_max_f32_e32 v26, v31, v31
	v_max_f32_e32 v31, 0, v26
	v_max_f32_e32 v26, v27, v27
	v_max_f32_e32 v37, 0, v26
	v_max_f32_e32 v26, v32, v32
	v_max_f32_e32 v32, 0, v26
	v_max_f32_e32 v26, v28, v28
	v_or_b32_e32 v34, 0x60, v82
	v_max_f32_e32 v38, 0, v26
	v_max_f32_e32 v26, v33, v33
	v_ashrrev_i32_e32 v35, 31, v34
	v_max_f32_e32 v33, 0, v26
	v_max_f32_e32 v26, v29, v29
	v_lshlrev_b64 v[34:35], 13, v[34:35]
	v_max_f32_e32 v39, 0, v26
	v_pk_mul_f32 v[26:27], v[30:31], v[30:31]
	v_pk_mul_f32 v[28:29], v[32:33], v[32:33]
	v_lshl_add_u64 v[34:35], s[80:81], 0, v[34:35]
	v_cvt_pk_bf16_f32 v26, v26, v27
	v_cvt_pk_bf16_f32 v27, v28, v29
	v_pk_mul_f32 v[28:29], v[36:37], v[36:37]
	v_pk_mul_f32 v[30:31], v[38:39], v[38:39]
	v_cvt_pk_bf16_f32 v28, v28, v29
	v_cvt_pk_bf16_f32 v29, v30, v31
	v_lshl_add_u64 v[30:31], v[34:35], 0, v[84:85]
	global_store_dwordx4 v[30:31], v[26:29], off
	v_max_f32_e32 v10, v10, v10
	v_max_f32_e32 v14, v14, v14
	v_max_f32_e32 v26, 0, v18
	v_max_f32_e32 v18, v23, v23
	v_max_f32_e32 v23, 0, v18
	v_max_f32_e32 v18, v19, v19
	v_max_f32_e32 v27, 0, v18
	v_max_f32_e32 v18, v24, v24
	v_max_f32_e32 v24, 0, v18
	v_max_f32_e32 v18, v20, v20
	v_max_f32_e32 v28, 0, v18
	v_max_f32_e32 v18, v25, v25
	v_max_f32_e32 v25, 0, v18
	v_max_f32_e32 v18, v21, v21
	v_max_f32_e32 v29, 0, v18
	v_pk_mul_f32 v[18:19], v[22:23], v[22:23]
	v_pk_mul_f32 v[20:21], v[24:25], v[24:25]
	v_cvt_pk_bf16_f32 v18, v18, v19
	v_cvt_pk_bf16_f32 v19, v20, v21
	v_pk_mul_f32 v[20:21], v[26:27], v[26:27]
	v_pk_mul_f32 v[22:23], v[28:29], v[28:29]
	v_cvt_pk_bf16_f32 v20, v20, v21
	v_cvt_pk_bf16_f32 v21, v22, v23
	global_store_dwordx4 v[30:31], v[18:21], off offset:64
	v_max_f32_e32 v14, 0, v14
	v_max_f32_e32 v2, v2, v2
	v_max_f32_e32 v20, 0, v10
	v_max_f32_e32 v10, v15, v15
	v_max_f32_e32 v15, 0, v10
	v_max_f32_e32 v10, v11, v11
	v_max_f32_e32 v21, 0, v10
	v_max_f32_e32 v10, v16, v16
	v_max_f32_e32 v16, 0, v10
	v_max_f32_e32 v10, v12, v12
	v_or_b32_e32 v18, 0x70, v82
	v_max_f32_e32 v22, 0, v10
	v_max_f32_e32 v10, v17, v17
	v_ashrrev_i32_e32 v19, 31, v18
	v_max_f32_e32 v17, 0, v10
	v_max_f32_e32 v10, v13, v13
	v_lshlrev_b64 v[18:19], 13, v[18:19]
	v_max_f32_e32 v23, 0, v10
	v_pk_mul_f32 v[10:11], v[14:15], v[14:15]
	v_pk_mul_f32 v[12:13], v[16:17], v[16:17]
	v_lshl_add_u64 v[18:19], s[80:81], 0, v[18:19]
	v_cvt_pk_bf16_f32 v10, v10, v11
	v_cvt_pk_bf16_f32 v11, v12, v13
	v_pk_mul_f32 v[12:13], v[20:21], v[20:21]
	v_pk_mul_f32 v[14:15], v[22:23], v[22:23]
	v_cvt_pk_bf16_f32 v12, v12, v13
	v_cvt_pk_bf16_f32 v13, v14, v15
	v_lshl_add_u64 v[14:15], v[18:19], 0, v[84:85]
	global_store_dwordx4 v[14:15], v[10:13], off
	v_max_f32_e32 v6, v6, v6
	v_max_f32_e32 v6, 0, v6
	v_max_f32_e32 v10, 0, v2
	v_max_f32_e32 v2, v7, v7
	v_max_f32_e32 v7, 0, v2
	v_max_f32_e32 v2, v3, v3
	v_max_f32_e32 v11, 0, v2
	v_max_f32_e32 v2, v8, v8
	v_max_f32_e32 v8, 0, v2
	v_max_f32_e32 v2, v4, v4
	v_max_f32_e32 v12, 0, v2
	v_max_f32_e32 v2, v9, v9
	v_max_f32_e32 v9, 0, v2
	v_max_f32_e32 v2, v5, v5
	v_max_f32_e32 v13, 0, v2
	v_pk_mul_f32 v[2:3], v[6:7], v[6:7]
	v_pk_mul_f32 v[4:5], v[8:9], v[8:9]
	v_cvt_pk_bf16_f32 v2, v2, v3
	v_cvt_pk_bf16_f32 v3, v4, v5
	v_pk_mul_f32 v[4:5], v[10:11], v[10:11]
	v_pk_mul_f32 v[6:7], v[12:13], v[12:13]
	v_cvt_pk_bf16_f32 v4, v4, v5
	v_cvt_pk_bf16_f32 v5, v6, v7
	s_movk_i32 s38, 0xff
	global_store_dwordx4 v[14:15], v[2:5], off offset:64
	s_branch .LBB0_1138
